# attention tiles: loop-invariant LDS address sums precomputed per unit; post-QK1 pad nop only on near tiles
# speedup vs baseline: 1.0169x; 1.0047x over previous
; template <int MODE>
; __device__ __forceinline__ void attn_unit(LAS unsigned char* lds, const Ptrs& P, int nq, int nt_block, int qpos0, bool sample, int h,
;                                           const float* relb  , const float* lamp, const float* subg, bf16_t* Obase  , int wv) {
;     ...
;     float mr1 = 0.f, l1 = 0.f, mr2 = 0.f, l2 = 0.f;
;     f32x16 o1a = {}, o1b = {}, o2a = {}, o2b = {};
;     f32x16 ng1, ng2;
; #pragma unroll
;     for (int r = 0; r < 16; ++r) { ng1[r] = cbias; ng2[r] = cbias; }
;     const int qmin = qpos0 + wid * 32, qposl = qmin + r32;
;     const int vrd = ((lane >> 4) & 1) * 32 + (lane & 3) * 8 + (4 * hi + ((lane & 15) >> 2)) * 64;
.LBB0_1187:
	v_lshlrev_b32_e32 v4, 1, v8
	v_and_b32_e32 v175, 32, v4
	v_lshlrev_b32_e32 v173, 2, v7
	v_lshrrev_b32_e32 v4, 2, v8
	s_lshl_b32 s30, s8, 2
	s_add_i32 s3, s3, s15
	v_and_or_b32 v4, v4, 3, v173
	v_mov_b32_e32 v18, v5
	v_mov_b32_e32 v19, v5
	s_ashr_i32 s4, s3, 6
	v_lshlrev_b32_e32 v174, 4, v9
	s_sub_i32 s3, 64, s30
	v_lshlrev_b32_e32 v176, 6, v4
	v_lshlrev_b32_e32 v178, 10, v7
	v_lshlrev_b32_e32 v179, 4, v6
	v_mov_b32_e32 v4, v5
	v_mov_b32_e32 v6, v5
	v_mov_b32_e32 v7, v5
	v_mov_b32_e32 v8, v5
	v_mov_b32_e32 v9, v5
	v_mov_b32_e32 v10, v5
	v_mov_b32_e32 v11, v5
	v_mov_b32_e32 v12, v5
	v_mov_b32_e32 v13, v5
	v_mov_b32_e32 v14, v5
	v_mov_b32_e32 v15, v5
	v_mov_b32_e32 v16, v5
	v_mov_b32_e32 v17, v5
	v_mov_b64_e32 v[66:67], v[18:19]
	v_mov_b64_e32 v[34:35], v[18:19]
	v_mov_b64_e32 v[50:51], v[18:19]
	v_ashrrev_i32_e32 v165, 31, v164
	s_lshl_b32 s23, s23, 10
	s_lshl_b32 s25, s2, 10
	s_lshr_b32 s34, s3, 1
	s_xor_b32 s35, s30, 63
	s_mov_b32 s30, 0
	v_mov_b32_e32 v177, 0
	v_mov_b64_e32 v[64:65], v[16:17]
	v_mov_b64_e32 v[62:63], v[14:15]
	v_mov_b64_e32 v[60:61], v[12:13]
	v_mov_b64_e32 v[58:59], v[10:11]
	v_mov_b64_e32 v[56:57], v[8:9]
	v_mov_b64_e32 v[54:55], v[6:7]
	v_mov_b64_e32 v[52:53], v[4:5]
	v_mov_b64_e32 v[32:33], v[16:17]
	v_mov_b64_e32 v[30:31], v[14:15]
	v_mov_b64_e32 v[28:29], v[12:13]
	v_mov_b64_e32 v[26:27], v[10:11]
	v_mov_b64_e32 v[24:25], v[8:9]
	v_mov_b64_e32 v[22:23], v[6:7]
	v_mov_b64_e32 v[20:21], v[4:5]
	v_mov_b64_e32 v[48:49], v[16:17]
	v_mov_b64_e32 v[46:47], v[14:15]
	v_mov_b64_e32 v[44:45], v[12:13]
	v_mov_b64_e32 v[42:43], v[10:11]
	v_mov_b64_e32 v[40:41], v[8:9]
	v_mov_b64_e32 v[38:39], v[6:7]
	v_mov_b64_e32 v[36:37], v[4:5]
	v_mov_b32_e32 v18, 0
	v_add3_u32 v247, v175, v176, v172

; #define LAS __attribute__((address_space(3)))
; __device__ __forceinline__ float xhalf_max(float m) { auto rr = __builtin_amdgcn_permlane32_swap(__float_as_uint(m), __float_as_uint(m), false, false); return fmaxf(__uint_as_float(rr[0]), __uint_as_float(rr[1])); }
; #define SB() __builtin_amdgcn_sched_barrier(0)
; __device__ __forceinline__ void softmax_def(f32x16& p0, f32x16& p1, bool first, float cb, float& mref, f32x16& negm, float& l, f32x16& oa, f32x16& ob) {
;     float a = fmaxf(fmaxf(p0[0], p0[1]), p1[0]), b = fmaxf(fmaxf(p0[2], p0[3]), p1[1]);
;     a = fmaxf(fmaxf(a, p1[2]), p1[3]);
; #pragma unroll
;     for (int r = 4; r < 16; r += 4) { a = fmaxf(fmaxf(a, p0[r]), p0[r + 1]); b = fmaxf(fmaxf(b, p0[r + 2]), p0[r + 3]); a = fmaxf(fmaxf(a, p1[r]), p1[r + 1]); b = fmaxf(fmaxf(b, p1[r + 2]), p1[r + 3]); }
;     const float rm = xhalf_max(fmaxf(a, b));
;     if (first || __any(rm > 16.f)) {
;         const float dl = first ? rm : fmaxf(rm, 0.f);
; template <int MODE>
; __device__ __forceinline__ void attn_unit(LAS unsigned char* lds, const Ptrs& P, int nq, int nt_block, int qpos0, bool sample, int h,
;                                           const float* relb  , const float* lamp, const float* subg, bf16_t* Obase  , int wv) {
;     ...
;             if (MODE == 1) {
;                 f32x16 p0, p1;
;                 bf16x8 kf[12];
; #pragma unroll
;                 for (int ks = 0; ks < 6; ++ks) { kf[2 * ks] = *(const LAS bf16x8*)(kb + ks * 2048); kf[2 * ks + 1] = *(const LAS bf16x8*)(kb + ks * 2048 + 512); }
;                 SB();
;                 p0 = __builtin_amdgcn_mfma_f32_32x32x16_bf16(kf[0], qf[0], ng1, 0, 0, 0);
;                 p1 = __builtin_amdgcn_mfma_f32_32x32x16_bf16(kf[1], qf[0], ng1, 0, 0, 0);
; #pragma unroll
;                 for (int ks = 1; ks < 6; ++ks) {
;                     p0 = __builtin_amdgcn_mfma_f32_32x32x16_bf16(kf[2 * ks], qf[ks], p0, 0, 0, 0);
;                     p1 = __builtin_amdgcn_mfma_f32_32x32x16_bf16(kf[2 * ks + 1], qf[ks], p1, 0, 0, 0);
;                 }
;                 bf16x8 vf[8]; VLOAD(vf);
;                 softmax_def(p0, p1, first, 0.f, mr1, ng1, l1, o1a, o1b);
.LBB0_1199:
	s_or_b32 s36, s37, s46
	s_cmp_ge_i32 s4, s36
	s_cselect_b64 s[30:31], -1, 0
	s_and_b64 s[30:31], s[38:39], s[30:31]
	s_andn2_b64 vcc, exec, s[30:31]
	s_cbranch_vccnz .LBB0_1198
	s_mul_i32 s30, s37, 0x5000
	s_add_i32 s30, s44, s30
	v_add3_u32 v4, s30, v178, v179
	ds_read_b128 v[6:9], v4
	ds_read_b128 v[10:13], v4 offset:512
	ds_read_b128 v[14:17], v4 offset:2048
	ds_read_b128 v[144:147], v4 offset:2560
	ds_read_b128 v[148:151], v4 offset:4096
	ds_read_b128 v[152:155], v4 offset:4608
	ds_read_b128 v[156:159], v4 offset:6144
	ds_read_b128 v[160:163], v4 offset:6656
	ds_read_b128 v[180:183], v4 offset:8192
	ds_read_b128 v[184:187], v4 offset:8704
	ds_read_b128 v[188:191], v4 offset:10240
	ds_read_b128 v[192:195], v4 offset:10752
	v_add_u32_e32 v4, s30, v247
	s_waitcnt lgkmcnt(11)
	v_mfma_f32_32x32x16_bf16 v[84:99], v[6:9], v[0:3], v[52:67]
	s_cmp_eq_u32 s36, 0
	s_cselect_b64 s[30:31], -1, 0
	s_cmp_lg_u32 s36, 0
	s_waitcnt lgkmcnt(10)
	v_mfma_f32_32x32x16_bf16 v[68:83], v[10:13], v[0:3], v[52:67]
	s_waitcnt lgkmcnt(9)
	v_mfma_f32_32x32x16_bf16 v[84:99], v[14:17], v[100:103], v[84:99]
	s_waitcnt lgkmcnt(8)
	v_mfma_f32_32x32x16_bf16 v[68:83], v[144:147], v[100:103], v[68:83]
	s_waitcnt lgkmcnt(7)
	v_mfma_f32_32x32x16_bf16 v[84:99], v[148:151], v[104:107], v[84:99]
	s_waitcnt lgkmcnt(6)
	v_mfma_f32_32x32x16_bf16 v[68:83], v[152:155], v[104:107], v[68:83]
	s_waitcnt lgkmcnt(5)
	v_mfma_f32_32x32x16_bf16 v[84:99], v[156:159], v[108:111], v[84:99]
	s_waitcnt lgkmcnt(4)
	v_mfma_f32_32x32x16_bf16 v[68:83], v[160:163], v[108:111], v[68:83]
	ds_read_b64_tr_b16 v[160:161], v4 offset:12288
	ds_read_b64_tr_b16 v[162:163], v4 offset:12800
	ds_read_b64_tr_b16 v[152:153], v4 offset:13312
	ds_read_b64_tr_b16 v[154:155], v4 offset:13824
	ds_read_b64_tr_b16 v[156:157], v4 offset:16384
	ds_read_b64_tr_b16 v[158:159], v4 offset:16896
	ds_read_b64_tr_b16 v[148:149], v4 offset:17408
	ds_read_b64_tr_b16 v[150:151], v4 offset:17920
	ds_read_b64_tr_b16 v[144:145], v4 offset:14336
	ds_read_b64_tr_b16 v[146:147], v4 offset:14848
	ds_read_b64_tr_b16 v[10:11], v4 offset:15360
	ds_read_b64_tr_b16 v[12:13], v4 offset:15872
	ds_read_b64_tr_b16 v[14:15], v4 offset:18432
	ds_read_b64_tr_b16 v[16:17], v4 offset:18944
	ds_read_b64_tr_b16 v[6:7], v4 offset:19456
	ds_read_b64_tr_b16 v[8:9], v4 offset:19968
	s_waitcnt lgkmcnt(14)
	v_mfma_f32_32x32x16_bf16 v[84:99], v[180:183], v[112:115], v[84:99]
	v_mfma_f32_32x32x16_bf16 v[68:83], v[184:187], v[112:115], v[68:83]
	v_mfma_f32_32x32x16_bf16 v[84:99], v[188:191], v[116:119], v[84:99]
	v_mfma_f32_32x32x16_bf16 v[68:83], v[192:195], v[116:119], v[68:83]
	s_nop 10
	v_max_f32_e32 v4, v84, v85
	v_max3_f32 v19, v86, v87, v69
	v_max3_f32 v4, v4, v68, v70
	v_max3_f32 v4, v4, v71, v88
	v_max3_f32 v19, v19, v90, v91
	v_max3_f32 v4, v4, v89, v72
	v_max3_f32 v19, v19, v74, v75
	v_max3_f32 v4, v4, v73, v92
	v_max3_f32 v19, v19, v94, v95
	v_max3_f32 v4, v4, v93, v76
	v_max3_f32 v19, v19, v78, v79
	v_max3_f32 v4, v4, v77, v96
	v_max3_f32 v19, v19, v98, v99
	v_max3_f32 v4, v4, v97, v80
	v_max3_f32 v19, v19, v82, v83
	v_max3_f32 v4, v4, v81, v19
	v_mov_b32_e32 v19, v4
	s_nop 1
	v_permlane32_swap_b32_e32 v4, v19
	v_max_f32_e32 v19, v4, v19
	s_cbranch_scc0 .LBB0_1208
	v_cmp_lt_f32_e32 vcc, s76, v19
	s_mov_b64 s[42:43], 0
	s_mov_b64 s[36:37], 0
	s_cbranch_vccz .LBB0_1207
	v_max_f32_e32 v4, v19, v19
	v_max_f32_e32 v4, 0, v4
	s_mov_b64 s[36:37], -1

; template <int MODE>
; __device__ __forceinline__ void attn_unit(LAS unsigned char* lds, const Ptrs& P, int nq, int nt_block, int qpos0, bool sample, int h,
;                                           const float* relb  , const float* lamp, const float* subg, bf16_t* Obase  , int wv) {
;     ...
;         cbias = relb[15 * 6 + h] * LOG2E;
;     }
;     const bf16_t* kg = P.K + (size_t)lane * P.ldk + wid * 8;
;     const bf16_t* krg = (MODE == 1) ? (P.Kr + (size_t)lane * 32 + (wid & 3) * 8) : nullptr;
;     const bf16_t* vg = P.V + (size_t)(16 * (wid & 3) + (lane >> 2)) * P.ldv + (wid >> 2) * 32 + (lane & 3) * 8;
;     const int kdst = wid * 1024 + lane * 16, krdst = (8 + (wid & 3)) * 1024 + lane * 16, vdst = KREG + wid * 1024 + lane * 16;
;     const int nst = (nt_block + 1) >> 1;
;     u32x4 kreg[2], vreg[2], krreg[2];
; #pragma unroll
;     for (int j = 0; j < 2; ++j) {
;         const int tt = (j < nt_block) ? j : (nt_block - 1);
;         kreg[j] = *(const u32x4*)(kg + (size_t)tt * 64 * P.ldk); vreg[j] = *(const u32x4*)(vg + (size_t)tt * 64 * P.ldv);
;         krreg[j] = (u32x4){0, 0, 0, 0};
;         if (MODE == 1) { if (wid < 4) krreg[j] = *(const u32x4*)(krg + (size_t)tt * 64 * 32); }
;     }
;     float mr1 = 0.f, l1 = 0.f, mr2 = 0.f, l2 = 0.f;
;     f32x16 o1a = {}, o1b = {}, o2a = {}, o2b = {};
;     f32x16 ng1, ng2;
; #pragma unroll
;     for (int r = 0; r < 16; ++r) { ng1[r] = cbias; ng2[r] = cbias; }
;     const int qmin = qpos0 + wid * 32, qposl = qmin + r32;
;     const int vrd = ((lane >> 4) & 1) * 32 + (lane & 3) * 8 + (4 * hi + ((lane & 15) >> 2)) * 64;
.LBB0_1221:
	s_or_b64 exec, exec, s[2:3]
	s_lshl_b32 s2, s22, 6
	s_mul_i32 s4, s24, 0xe40
	v_readlane_b32 s26, v251, 55
	s_mul_hi_u32 s3, s24, 0xe40
	v_readlane_b32 s27, v251, 56
	s_add_u32 s24, s26, s4
	s_addc_u32 s3, s27, s3
	s_lshl_b32 s4, s2, 1
	s_add_u32 s2, s24, s4
	s_addc_u32 s3, s3, 0
	s_lshl_b32 s24, s8, 2
	s_add_i32 s8, s23, s15
	s_mov_b32 s23, s83
	v_readlane_b32 s40, v255, 18
	s_ashr_i32 s15, s8, 6
	s_lshl_b64 s[22:23], s[22:23], 2
	v_readlane_b32 s42, v255, 20
	v_and_b32_e32 v4, 63, v7
	v_readlane_b32 s43, v255, 21
	s_add_u32 s22, s42, s22
	s_addc_u32 s23, s43, s23
	v_mul_u32_u24_e32 v8, 0x720, v4
	global_load_dword v13, v5, s[22:23] offset:360
	v_lshlrev_b32_e32 v8, 1, v8
	v_mov_b32_e32 v9, v5
	s_lshl_b32 s22, s25, 3
	v_lshl_add_u64 v[8:9], s[2:3], 0, v[8:9]
	s_ashr_i32 s23, s22, 31
	v_lshl_add_u64 v[224:225], s[22:23], 1, v[8:9]
	s_lshl_b32 s22, s25, 4
	v_lshrrev_b32_e32 v8, 2, v4
	v_and_or_b32 v8, s22, 48, v8
	v_mul_u32_u24_e32 v8, 0x720, v8
	v_lshlrev_b32_e32 v8, 1, v8
	v_mov_b32_e32 v9, v5
	v_lshl_add_u64 v[8:9], s[2:3], 0, v[8:9]
	s_ashr_i32 s2, s28, 3
	s_andn2_b32 s2, s2, 31
	v_lshlrev_b32_e32 v10, 3, v7
	s_ashr_i32 s3, s2, 31
	v_and_b32_e32 v217, 24, v10
	v_lshl_add_u64 v[8:9], s[2:3], 1, v[8:9]
	v_lshlrev_b32_e32 v10, 1, v217
	v_mov_b32_e32 v11, v5
	v_lshl_add_u64 v[226:227], v[8:9], 0, v[10:11]
	s_mov_b32 s2, 0x39000
	v_add_co_u32_e32 v8, vcc, s2, v226
	v_lshlrev_b32_e32 v219, 4, v4
	s_nop 0
	v_addc_co_u32_e32 v9, vcc, 0, v227, vcc
	v_add_co_u32_e32 v10, vcc, s2, v224
	v_lshlrev_b32_e32 v4, 1, v7
	s_nop 0
	v_addc_co_u32_e32 v11, vcc, 0, v225, vcc
	global_load_dwordx4 v[194:197], v[226:227], off offset:1536
	global_load_dwordx4 v[198:201], v[224:225], off offset:768
	global_load_dwordx4 v[202:205], v[8:9], off offset:1536
	global_load_dwordx4 v[206:209], v[10:11], off offset:768
	v_lshlrev_b32_e32 v216, 2, v6
	v_lshrrev_b32_e32 v14, 2, v7
	v_and_b32_e32 v230, 32, v4
	v_and_or_b32 v4, v14, 3, v216
	v_lshlrev_b32_e32 v231, 6, v4
	v_or_b32_e32 v4, s8, v12
	v_mov_b32_e32 v20, v5
	v_mov_b32_e32 v21, v5
	v_lshlrev_b32_e32 v228, 10, v6
	v_lshlrev_b32_e32 v229, 4, v12
	v_mov_b32_e32 v6, v5
	v_mov_b32_e32 v7, v5
	v_mov_b32_e32 v8, v5
	v_mov_b32_e32 v9, v5
	v_mov_b32_e32 v10, v5
	v_mov_b32_e32 v11, v5
	v_sub_u32_e32 v4, v216, v4
	s_sub_i32 s3, 64, s24
	v_mov_b32_e32 v12, v5
	v_mov_b32_e32 v14, v5
	v_mov_b32_e32 v15, v5
	v_mov_b32_e32 v16, v5
	v_mov_b32_e32 v17, v5
	v_mov_b32_e32 v18, v5
	v_mov_b32_e32 v19, v5
	v_ashrrev_i32_e32 v223, 31, v222
	s_mov_b32 s2, 0
	s_lshl_b32 s34, s25, 10
	s_xor_b32 s35, s24, 63
	v_add_u32_e32 v232, 0xc0, v4
	s_lshr_b32 s36, s3, 1
	v_mov_b32_e32 v218, 0
	v_mov_b32_e32 v233, 0
	v_mov_b32_e32 v234, 0
	v_readlane_b32 s41, v255, 19
	v_readlane_b32 s44, v255, 22
	v_readlane_b32 s45, v255, 23
	v_readlane_b32 s46, v255, 24
	v_readlane_b32 s47, v255, 25
	s_waitcnt vmcnt(4)
	v_mul_f32_e32 v70, 0x3fb8aa3b, v13
	v_mov_b32_e32 v84, v70
	v_mov_b32_e32 v85, v70
	v_mov_b32_e32 v71, v70
	v_mov_b32_e32 v72, v70
	v_mov_b32_e32 v73, v70
	v_mov_b32_e32 v74, v70
	v_mov_b32_e32 v75, v70
	v_mov_b32_e32 v76, v70
	v_mov_b32_e32 v77, v70
	v_mov_b32_e32 v78, v70
	v_mov_b32_e32 v79, v70
	v_mov_b32_e32 v80, v70
	v_mov_b32_e32 v81, v70
	v_mov_b32_e32 v82, v70
	v_mov_b32_e32 v83, v70
	v_mov_b32_e32 v13, v5
	v_mov_b64_e32 v[100:101], v[84:85]
	v_mov_b64_e32 v[116:117], v[84:85]
	v_mov_b64_e32 v[68:69], v[20:21]
	v_mov_b64_e32 v[36:37], v[20:21]
	v_mov_b64_e32 v[52:53], v[20:21]
	v_mov_b64_e32 v[98:99], v[82:83]
	v_mov_b64_e32 v[96:97], v[80:81]
	v_mov_b64_e32 v[94:95], v[78:79]
	v_mov_b64_e32 v[92:93], v[76:77]
	v_mov_b64_e32 v[90:91], v[74:75]
	v_mov_b64_e32 v[88:89], v[72:73]
	v_mov_b64_e32 v[86:87], v[70:71]
	v_mov_b64_e32 v[114:115], v[82:83]
	v_mov_b64_e32 v[112:113], v[80:81]
	v_mov_b64_e32 v[110:111], v[78:79]
	v_mov_b64_e32 v[108:109], v[76:77]
	v_mov_b64_e32 v[106:107], v[74:75]
	v_mov_b64_e32 v[104:105], v[72:73]
	v_mov_b64_e32 v[102:103], v[70:71]
	v_mov_b64_e32 v[66:67], v[18:19]
	v_mov_b64_e32 v[64:65], v[16:17]
	v_mov_b64_e32 v[62:63], v[14:15]
	v_mov_b64_e32 v[60:61], v[12:13]
	v_mov_b64_e32 v[58:59], v[10:11]
	v_mov_b64_e32 v[56:57], v[8:9]
	v_mov_b64_e32 v[54:55], v[6:7]
	v_mov_b64_e32 v[34:35], v[18:19]
	v_mov_b64_e32 v[32:33], v[16:17]
	v_mov_b64_e32 v[30:31], v[14:15]
	v_mov_b64_e32 v[28:29], v[12:13]
	v_mov_b64_e32 v[26:27], v[10:11]
	v_mov_b64_e32 v[24:25], v[8:9]
	v_mov_b64_e32 v[22:23], v[6:7]
	v_mov_b64_e32 v[50:51], v[18:19]
	v_mov_b64_e32 v[48:49], v[16:17]
	v_mov_b64_e32 v[46:47], v[14:15]
	v_mov_b64_e32 v[44:45], v[12:13]
	v_mov_b64_e32 v[42:43], v[10:11]
	v_mov_b64_e32 v[40:41], v[8:9]
	v_mov_b64_e32 v[38:39], v[6:7]
	v_mov_b32_e32 v71, 0
	v_add_u32_e32 v244, v228, v229
	v_add3_u32 v245, v230, v231, v217

; #define LAS __attribute__((address_space(3)))
; template <int MODE>
; __device__ __forceinline__ void attn_unit(LAS unsigned char* lds, const Ptrs& P, int nq, int nt_block, int qpos0, bool sample, int h,
;                                           const float* relb  , const float* lamp, const float* subg, bf16_t* Obase  , int wv) {
;     ...
;                 const int k0 = t * 64;
;                 const bool farT = (k0 + 63 - qmin <= -91);
;                 const int ib = k0 - qposl + 192 + 4 * hi;
;                 bf16x8 pa[4], pb[4];
;                 bf16x8 kf[4], kg2[4];
; #pragma unroll
;                 for (int ks = 0; ks < 2; ++ks) { kf[2 * ks] = *(const LAS bf16x8*)(kb + ks * 2048); kf[2 * ks + 1] = *(const LAS bf16x8*)(kb + ks * 2048 + 512); }
;                 {
;                     f32x16 p0, p1;
;                     if (farT) {
;                         p0 = __builtin_amdgcn_mfma_f32_32x32x16_bf16(kf[0], qf[0], ng1, 0, 0, 0);
;                         p1 = __builtin_amdgcn_mfma_f32_32x32x16_bf16(kf[1], qf[0], ng1, 0, 0, 0);
;                     } else {
;                         const float nb = ng1[0] - cbias;
; #pragma unroll
;                         for (int r = 0; r < 16; ++r) { const int idx = ib + (r & 3) + 8 * (r >> 2); p0[r] = bt[idx] + nb; p1[r] = bt[idx + 32] + nb; }
;                         p0 = __builtin_amdgcn_mfma_f32_32x32x16_bf16(kf[0], qf[0], p0, 0, 0, 0);
;                         p1 = __builtin_amdgcn_mfma_f32_32x32x16_bf16(kf[1], qf[0], p1, 0, 0, 0);
;                     }
.LBB0_1226:
	s_or_b32 s28, s24, s41
	s_cmp_ge_i32 s15, s28
	s_cselect_b64 s[2:3], -1, 0
	s_and_b64 s[2:3], s[38:39], s[2:3]
	s_andn2_b64 vcc, exec, s[2:3]
	s_cbranch_vccnz .LBB0_1225
	s_mul_i32 s2, s24, 0x5000
	s_add_i32 s42, s37, s2
	v_add_u32_e32 v4, s42, v244
	ds_read_b128 v[76:79], v4
	ds_read_b128 v[80:83], v4 offset:512
	ds_read_b128 v[72:75], v4 offset:2048
	ds_read_b128 v[150:153], v4 offset:2560
	s_lshl_b32 s2, s28, 6
	s_sub_i32 s3, s2, s8
	s_cmpk_gt_i32 s3, 0xff66
	s_cselect_b64 s[26:27], -1, 0
	s_mov_b64 s[2:3], -1
	s_and_b64 vcc, exec, s[26:27]
	s_cbranch_vccz .Lm0p_far1
	s_lshl_b32 s2, s28, 6
	v_add_u32_e32 v84, s2, v232
	v_lshl_add_u32 v84, v84, 2, 0
	v_add_u32_e32 v85, 0x14000, v84
	ds_read2_b32 v[118:119], v85 offset1:1
	ds_read2_b32 v[120:121], v85 offset0:2 offset1:3
	ds_read2_b32 v[122:123], v85 offset0:8 offset1:9
	ds_read2_b32 v[124:125], v85 offset0:10 offset1:11
	ds_read2_b32 v[126:127], v85 offset0:16 offset1:17
	ds_read2_b32 v[128:129], v85 offset0:18 offset1:19
	ds_read2_b32 v[130:131], v85 offset0:24 offset1:25
	ds_read2_b32 v[132:133], v85 offset0:26 offset1:27
	ds_read2_b32 v[154:155], v85 offset0:32 offset1:33
	ds_read2_b32 v[136:137], v85 offset0:34 offset1:35
	ds_read2_b32 v[138:139], v85 offset0:40 offset1:41
	ds_read2_b32 v[140:141], v85 offset0:42 offset1:43
	ds_read2_b32 v[142:143], v85 offset0:48 offset1:49
	ds_read2_b32 v[144:145], v85 offset0:50 offset1:51
	ds_read2_b32 v[146:147], v85 offset0:56 offset1:57
	ds_read2_b32 v[148:149], v85 offset0:58 offset1:59
	v_sub_f32_e32 v134, v102, v70
	s_waitcnt lgkmcnt(8)
	v_pk_add_f32 v[132:133], v[134:135], v[132:133] op_sel_hi:[0,1]
	v_pk_add_f32 v[130:131], v[134:135], v[130:131] op_sel_hi:[0,1]
	v_pk_add_f32 v[128:129], v[134:135], v[128:129] op_sel_hi:[0,1]
	v_pk_add_f32 v[126:127], v[134:135], v[126:127] op_sel_hi:[0,1]
	v_pk_add_f32 v[124:125], v[134:135], v[124:125] op_sel_hi:[0,1]
	v_pk_add_f32 v[122:123], v[134:135], v[122:123] op_sel_hi:[0,1]
	v_pk_add_f32 v[120:121], v[134:135], v[120:121] op_sel_hi:[0,1]
	v_pk_add_f32 v[118:119], v[134:135], v[118:119] op_sel_hi:[0,1]
	s_waitcnt lgkmcnt(0)
	v_pk_add_f32 v[148:149], v[134:135], v[148:149] op_sel_hi:[0,1]
	v_pk_add_f32 v[146:147], v[134:135], v[146:147] op_sel_hi:[0,1]
	v_pk_add_f32 v[144:145], v[134:135], v[144:145] op_sel_hi:[0,1]
	v_pk_add_f32 v[142:143], v[134:135], v[142:143] op_sel_hi:[0,1]
	v_pk_add_f32 v[140:141], v[134:135], v[140:141] op_sel_hi:[0,1]
	v_pk_add_f32 v[138:139], v[134:135], v[138:139] op_sel_hi:[0,1]
	v_pk_add_f32 v[136:137], v[134:135], v[136:137] op_sel_hi:[0,1]
	v_pk_add_f32 v[134:135], v[134:135], v[154:155] op_sel_hi:[0,1]
	v_mfma_f32_32x32x16_bf16 v[118:133], v[76:79], v[0:3], v[118:133]
	s_mov_b64 s[2:3], 0
	v_mfma_f32_32x32x16_bf16 v[134:149], v[80:83], v[0:3], v[134:149]

; __device__ __forceinline__ void softmax_def(f32x16& p0, f32x16& p1, bool first, float cb, float& mref, f32x16& negm, float& l, f32x16& oa, f32x16& ob) {
;     float a = fmaxf(fmaxf(p0[0], p0[1]), p1[0]), b = fmaxf(fmaxf(p0[2], p0[3]), p1[1]);
;     a = fmaxf(fmaxf(a, p1[2]), p1[3]);
; #pragma unroll
;     for (int r = 4; r < 16; r += 4) { a = fmaxf(fmaxf(a, p0[r]), p0[r + 1]); b = fmaxf(fmaxf(b, p0[r + 2]), p0[r + 3]); a = fmaxf(fmaxf(a, p1[r]), p1[r + 1]); b = fmaxf(fmaxf(b, p1[r + 2]), p1[r + 3]); }
;     const float rm = xhalf_max(fmaxf(a, b));
; template <int MODE>
; __device__ __forceinline__ void attn_unit(LAS unsigned char* lds, const Ptrs& P, int nq, int nt_block, int qpos0, bool sample, int h,
;                                           const float* relb  , const float* lamp, const float* subg, bf16_t* Obase  , int wv) {
;     ...
;                     p0 = __builtin_amdgcn_mfma_f32_32x32x16_bf16(kf[2], qf[1], p0, 0, 0, 0);
;                     p1 = __builtin_amdgcn_mfma_f32_32x32x16_bf16(kf[3], qf[1], p1, 0, 0, 0);
; #pragma unroll
;                     for (int ks = 0; ks < 2; ++ks) { kg2[2 * ks] = *(const LAS bf16x8*)(kb + 4096 + ks * 2048); kg2[2 * ks + 1] = *(const LAS bf16x8*)(kb + 4096 + ks * 2048 + 512); }
;                     softmax_def(p0, p1, first, cbias, mr1, ng1, l1, o1a, o1b);
;                     pack_p(p0, p1, pa);
;                 }
;                 bf16x8 vf[8];
;                 {
;                     f32x16 s0, s1;
;                     if (farT) {
;                         s0 = __builtin_amdgcn_mfma_f32_32x32x16_bf16(kg2[0], qf[2], ng2, 0, 0, 0);
;                         s1 = __builtin_amdgcn_mfma_f32_32x32x16_bf16(kg2[1], qf[2], ng2, 0, 0, 0);
;                     } else {
;                         const float nb = ng2[0] - cbias;
; #pragma unroll
;                         for (int r = 0; r < 16; ++r) { const int idx = ib + (r & 3) + 8 * (r >> 2); s0[r] = bt[idx] + nb; s1[r] = bt[idx + 32] + nb; }
;                         s0 = __builtin_amdgcn_mfma_f32_32x32x16_bf16(kg2[0], qf[2], s0, 0, 0, 0);
;                         s1 = __builtin_amdgcn_mfma_f32_32x32x16_bf16(kg2[1], qf[2], s1, 0, 0, 0);
;                     }
;                     s0 = __builtin_amdgcn_mfma_f32_32x32x16_bf16(kg2[2], qf[3], s0, 0, 0, 0);
;                     s1 = __builtin_amdgcn_mfma_f32_32x32x16_bf16(kg2[3], qf[3], s1, 0, 0, 0);
.LBB0_1231:
	s_waitcnt lgkmcnt(1)
	v_mfma_f32_32x32x16_bf16 v[118:133], v[72:75], v[182:185], v[118:133]
	ds_read_b128 v[80:83], v4 offset:4096
	ds_read_b128 v[210:213], v4 offset:4608
	ds_read_b128 v[76:79], v4 offset:6144
	ds_read_b128 v[72:75], v4 offset:6656
	s_cmp_eq_u32 s28, 0
	s_cselect_b64 s[24:25], -1, 0
	s_cmp_lg_u32 s28, 0
	s_cselect_b64 s[2:3], -1, 0
	s_and_b64 vcc, exec, s[2:3]
	s_waitcnt lgkmcnt(4)
	v_mfma_f32_32x32x16_bf16 v[134:149], v[150:153], v[182:185], v[134:149]
	s_cmp_lg_u64 s[26:27], 0
	s_cbranch_scc1 .Lqk2h_near_p
	s_waitcnt lgkmcnt(3)
	v_mfma_f32_32x32x16_bf16 v[166:181], v[80:83], v[186:189], v[86:101]
	s_waitcnt lgkmcnt(2)
	v_mfma_f32_32x32x16_bf16 v[150:165], v[210:213], v[186:189], v[86:101]
	s_waitcnt lgkmcnt(1)
	v_mfma_f32_32x32x16_bf16 v[166:181], v[76:79], v[190:193], v[166:181]
	s_waitcnt lgkmcnt(0)
	v_mfma_f32_32x32x16_bf16 v[150:165], v[72:75], v[190:193], v[150:165]
	v_max_f32_e32 v4, v118, v119
	s_nop 0
.Lqk2h_join_p:
	v_max3_f32 v85, v120, v121, v135
	v_max3_f32 v4, v4, v134, v136
	v_max3_f32 v4, v4, v137, v122
	v_max3_f32 v85, v85, v124, v125
	v_max3_f32 v4, v4, v123, v138
	v_max3_f32 v85, v85, v140, v141
	v_max3_f32 v4, v4, v139, v126
	v_max3_f32 v85, v85, v128, v129
	v_max3_f32 v4, v4, v127, v142
	v_max3_f32 v85, v85, v144, v145
	v_max3_f32 v4, v4, v143, v130
	v_max3_f32 v85, v85, v132, v133
	v_max3_f32 v4, v4, v131, v146
	v_max3_f32 v85, v85, v148, v149
	v_max3_f32 v4, v4, v147, v85
	v_mov_b32_e32 v85, v4
	s_nop 1
	v_permlane32_swap_b32_e32 v4, v85
	v_max_f32_e32 v85, v4, v85
	s_cbranch_vccz .LBB0_1236
	v_cmp_lt_f32_e32 vcc, s76, v85
	s_mov_b64 s[30:31], 0
	s_mov_b64 s[28:29], 0
	s_cbranch_vccz .LBB0_1239
	v_max_f32_e32 v4, v85, v85
	v_max_f32_e32 v4, 0, v4
	s_mov_b64 s[28:29], -1

; __device__ __forceinline__ void softmax_def(f32x16& p0, f32x16& p1, bool first, float cb, float& mref, f32x16& negm, float& l, f32x16& oa, f32x16& ob) {
;     ...
;     for (int r = 0; r < 16; ++r) { p0[r] = __builtin_amdgcn_exp2f(p0[r]); p1[r] = __builtin_amdgcn_exp2f(p1[r]); }
; #pragma unroll
;     for (int r = 0; r < 16; r += 2) { s0 += p0[r]; s1 += p0[r + 1]; s2 += p1[r]; s3 += p1[r + 1]; }
;     l += (s0 + s1) + (s2 + s3);
; template <int MODE>
; __device__ __forceinline__ void attn_unit(LAS unsigned char* lds, const Ptrs& P, int nq, int nt_block, int qpos0, bool sample, int h,
;                                           const float* relb  , const float* lamp, const float* subg, bf16_t* Obase  , int wv) {
;     ...
;                     softmax_def(s0, s1, first, cbias, mr2, ng2, l2, o2a, o2b);
;                     pack_p(s0, s1, pb);
;                 }
;                 VLOADH(vf, 0); VLOADH(vf, 1);
; #pragma unroll
;                 for (int ks = 0; ks < 4; ++ks) {
;                     o1a = __builtin_amdgcn_mfma_f32_32x32x16_bf16(vf[2 * ks], pa[ks], o1a, 0, 0, 0);
;                     o1b = __builtin_amdgcn_mfma_f32_32x32x16_bf16(vf[2 * ks + 1], pa[ks], o1b, 0, 0, 0);
;                     o2a = __builtin_amdgcn_mfma_f32_32x32x16_bf16(vf[2 * ks], pb[ks], o2a, 0, 0, 0);
;                     o2b = __builtin_amdgcn_mfma_f32_32x32x16_bf16(vf[2 * ks + 1], pb[ks], o2b, 0, 0, 0);
;                 }
.LBB0_1250:
	v_exp_f32_e32 v75, v119
	v_exp_f32_e32 v79, v121
	v_exp_f32_e32 v4, v134
	v_exp_f32_e32 v83, v123
	v_exp_f32_e32 v72, v135
	v_exp_f32_e32 v74, v136
	v_exp_f32_e32 v119, v125
	v_exp_f32_e32 v73, v118
	v_exp_f32_e32 v76, v137
	v_exp_f32_e32 v78, v138
	v_exp_f32_e32 v125, v127
	v_exp_f32_e32 v77, v120
	v_exp_f32_e32 v80, v139
	v_exp_f32_e32 v82, v140
	v_add_f32_e32 v136, v79, v75
	v_exp_f32_e32 v81, v122
	v_exp_f32_e32 v85, v124
	v_exp_f32_e32 v118, v141
	v_exp_f32_e32 v124, v142
	v_add_f32_e32 v136, v83, v136
	v_exp_f32_e32 v134, v143
	v_add_f32_e32 v137, v74, v4
	v_add_f32_e32 v136, v119, v136
	v_exp_f32_e32 v120, v148
	v_exp_f32_e32 v121, v133
	v_add_f32_e32 v138, v76, v72
	v_add_f32_e32 v137, v78, v137
	v_add_f32_e32 v148, v125, v136
	v_add_f32_e32 v133, v77, v73
	v_add_f32_e32 v138, v80, v138
	v_add_f32_e32 v137, v82, v137
	v_add_u32_e32 v210, s42, v245
	v_exp_f32_e32 v123, v126
	v_exp_f32_e32 v127, v128
	v_exp_f32_e32 v84, v144
	v_exp_f32_e32 v126, v145
	v_exp_f32_e32 v135, v130
	v_exp_f32_e32 v128, v146
	v_exp_f32_e32 v130, v147
	v_exp_f32_e32 v122, v149
	v_add_f32_e32 v133, v81, v133
	v_add_f32_e32 v140, v118, v138
	v_add_f32_e32 v149, v124, v137
	ds_read_b64_tr_b16 v[136:137], v210 offset:12288
	ds_read_b64_tr_b16 v[138:139], v210 offset:12800
	ds_read_b64_tr_b16 v[144:145], v210 offset:16384
	ds_read_b64_tr_b16 v[146:147], v210 offset:16896
	v_add_f32_e32 v133, v85, v133
	v_add_f32_e32 v211, v134, v140
	v_cvt_pk_bf16_f32 v140, v73, v75
	v_cvt_pk_bf16_f32 v141, v77, v79
	v_cvt_pk_bf16_f32 v142, v81, v83
	v_cvt_pk_bf16_f32 v143, v85, v119
	v_exp_f32_e32 v119, v166
	v_exp_f32_e32 v79, v167
	v_exp_f32_e32 v77, v168
	v_exp_f32_e32 v75, v169
	v_exp_f32_e32 v73, v170
	v_exp_f32_e32 v85, v171
	v_exp_f32_e32 v83, v172
	v_exp_f32_e32 v81, v173
	v_exp_f32_e32 v129, v129
	v_exp_f32_e32 v131, v131
	v_exp_f32_e32 v132, v132
	s_waitcnt lgkmcnt(2)
	v_mfma_f32_32x32x16_bf16 v[38:53], v[136:139], v[140:143], v[38:53]
	v_add_f32_e32 v133, v123, v133
	v_add_f32_e32 v133, v127, v133
	v_add_f32_e32 v148, v129, v148
	v_add_f32_e32 v133, v135, v133
	v_add_f32_e32 v148, v131, v148
	v_add_f32_e32 v167, v132, v133
	v_exp_f32_e32 v133, v176
	s_waitcnt lgkmcnt(0)
	v_mfma_f32_32x32x16_bf16 v[22:37], v[144:147], v[140:143], v[22:37]
	v_cvt_pk_bf16_f32 v140, v119, v79
	v_cvt_pk_bf16_f32 v141, v77, v75
	v_cvt_pk_bf16_f32 v142, v73, v85
	v_cvt_pk_bf16_f32 v143, v83, v81
	v_add_f32_e32 v149, v84, v149
	v_add_f32_e32 v149, v128, v149
	s_xor_b64 s[2:3], s[22:23], -1
	v_mfma_f32_32x32x16_bf16 v[54:69], v[136:139], v[140:143], v[54:69]
	v_add_f32_e32 v136, v126, v211
	v_add_f32_e32 v166, v130, v136
	ds_read_b64_tr_b16 v[136:137], v210 offset:13312
	ds_read_b64_tr_b16 v[138:139], v210 offset:13824
	v_mfma_f32_32x32x16_bf16 v[6:21], v[144:147], v[140:143], v[6:21]
	ds_read_b64_tr_b16 v[144:145], v210 offset:17408
	ds_read_b64_tr_b16 v[146:147], v210 offset:17920
	v_cvt_pk_bf16_f32 v140, v123, v125
	v_cvt_pk_bf16_f32 v141, v127, v129
	v_cvt_pk_bf16_f32 v142, v135, v131
	v_cvt_pk_bf16_f32 v143, v132, v121
	v_add_f32_e32 v132, v121, v148
	v_exp_f32_e32 v131, v174
	v_exp_f32_e32 v135, v175
	v_exp_f32_e32 v123, v177
	v_exp_f32_e32 v121, v178
	v_exp_f32_e32 v129, v179
	v_exp_f32_e32 v127, v180
	v_exp_f32_e32 v125, v181
	s_waitcnt lgkmcnt(2)
	v_mfma_f32_32x32x16_bf16 v[38:53], v[136:139], v[140:143], v[38:53]
	v_add_f32_e32 v148, v120, v149
	v_add_f32_e32 v132, v132, v167
	s_waitcnt lgkmcnt(0)
	v_mfma_f32_32x32x16_bf16 v[22:37], v[144:147], v[140:143], v[22:37]
	v_cvt_pk_bf16_f32 v140, v131, v135
	v_cvt_pk_bf16_f32 v141, v133, v123
	v_cvt_pk_bf16_f32 v142, v121, v129
	v_cvt_pk_bf16_f32 v143, v127, v125
	s_nop 1
	v_mfma_f32_32x32x16_bf16 v[54:69], v[136:139], v[140:143], v[54:69]
	v_add_f32_e32 v136, v122, v166
	v_add_f32_e32 v136, v136, v148
	v_add_f32_e32 v132, v136, v132
	ds_read_b64_tr_b16 v[136:137], v210 offset:14336
	ds_read_b64_tr_b16 v[138:139], v210 offset:14848
	ds_read_b64_tr_b16 v[166:167], v210 offset:18432
	ds_read_b64_tr_b16 v[168:169], v210 offset:18944
	v_add_f32_e32 v71, v71, v132
	v_exp_f32_e32 v132, v160
	v_mfma_f32_32x32x16_bf16 v[6:21], v[144:147], v[140:143], v[6:21]
	v_cvt_pk_bf16_f32 v142, v78, v80
	v_cvt_pk_bf16_f32 v143, v82, v118
	v_exp_f32_e32 v118, v150
	v_exp_f32_e32 v78, v151
	v_cvt_pk_bf16_f32 v140, v4, v72
	v_cvt_pk_bf16_f32 v141, v74, v76
	v_cvt_pk_bf16_f32 v145, v84, v126
	v_exp_f32_e32 v76, v152
	v_exp_f32_e32 v74, v153
	v_exp_f32_e32 v72, v154
	v_exp_f32_e32 v84, v155
	v_exp_f32_e32 v82, v156
	v_exp_f32_e32 v80, v157
	v_cvt_pk_bf16_f32 v144, v124, v134
	s_waitcnt lgkmcnt(2)
	v_mfma_f32_32x32x16_bf16 v[38:53], v[136:139], v[140:143], v[38:53]
	v_cvt_pk_bf16_f32 v146, v128, v130
	v_exp_f32_e32 v130, v158
	v_exp_f32_e32 v134, v159
	v_cvt_pk_bf16_f32 v147, v120, v122
	v_exp_f32_e32 v122, v161
	v_exp_f32_e32 v120, v162
	v_exp_f32_e32 v128, v163
	s_waitcnt lgkmcnt(0)
	v_mfma_f32_32x32x16_bf16 v[22:37], v[166:169], v[140:143], v[22:37]
	v_cvt_pk_bf16_f32 v140, v118, v78
	v_cvt_pk_bf16_f32 v141, v76, v74
	v_cvt_pk_bf16_f32 v142, v72, v84
	v_cvt_pk_bf16_f32 v143, v82, v80
	v_pk_add_f32 v[76:77], v[76:77], v[118:119]
	v_pk_add_f32 v[74:75], v[74:75], v[78:79]
	v_mfma_f32_32x32x16_bf16 v[54:69], v[136:139], v[140:143], v[54:69]
	v_add_f32_e64 v72, v72, v76
	v_add_f32_e64 v73, v73, v77
	v_add_f32_e64 v74, v84, v74
	v_add_f32_e64 v75, v85, v75
	v_exp_f32_e32 v126, v164
	v_exp_f32_e32 v124, v165
	v_pk_add_f32 v[72:73], v[82:83], v[72:73]
	v_pk_add_f32 v[74:75], v[80:81], v[74:75]
	v_pk_add_f32 v[72:73], v[130:131], v[72:73]
	v_mfma_f32_32x32x16_bf16 v[6:21], v[166:169], v[140:143], v[6:21]
	v_add_f32_e64 v76, v134, v74
	v_add_f32_e64 v77, v135, v75
	ds_read_b64_tr_b16 v[136:137], v210 offset:15360
	ds_read_b64_tr_b16 v[138:139], v210 offset:15872
	ds_read_b64_tr_b16 v[140:141], v210 offset:19456
	ds_read_b64_tr_b16 v[142:143], v210 offset:19968
	v_pk_add_f32 v[78:79], v[132:133], v[72:73]
	v_pk_add_f32 v[76:77], v[122:123], v[76:77]
	v_pk_add_f32 v[78:79], v[120:121], v[78:79]
	v_pk_add_f32 v[76:77], v[128:129], v[76:77]
	v_pk_add_f32 v[78:79], v[126:127], v[78:79]
	v_pk_add_f32 v[76:77], v[124:125], v[76:77]
	v_cvt_pk_bf16_f32 v72, v130, v134
	v_pk_add_f32 v[76:77], v[76:77], v[78:79]
	v_cvt_pk_bf16_f32 v73, v132, v122
	v_cvt_pk_bf16_f32 v74, v120, v128
	v_cvt_pk_bf16_f32 v75, v126, v124
	v_add_f32_e32 v4, v76, v77
	s_waitcnt lgkmcnt(2)
	v_mfma_f32_32x32x16_bf16 v[38:53], v[136:139], v[144:147], v[38:53]
	v_add_f32_e32 v218, v218, v4
	s_waitcnt lgkmcnt(0)
	v_mfma_f32_32x32x16_bf16 v[22:37], v[140:143], v[144:147], v[22:37]
	v_mfma_f32_32x32x16_bf16 v[54:69], v[136:139], v[72:75], v[54:69]
	v_mfma_f32_32x32x16_bf16 v[6:21], v[140:143], v[72:75], v[6:21]
	s_mov_b32 s24, 1
	s_mov_b64 s[22:23], 0
	s_and_b64 vcc, exec, s[2:3]
	s_cbranch_vccz .LBB0_1226
	s_branch .LBB0_1252

; __device__ __forceinline__ void softmax_def(f32x16& p0, f32x16& p1, bool first, float cb, float& mref, f32x16& negm, float& l, f32x16& oa, f32x16& ob) {
;     float a = fmaxf(fmaxf(p0[0], p0[1]), p1[0]), b = fmaxf(fmaxf(p0[2], p0[3]), p1[1]);
.Lqk2h_near_p:
	v_max_f32_e32 v4, v118, v119
	s_nop 9
	s_branch .Lqk2h_join_p
